# P4 attention kt loops: wave-uniform branch to a copy without the causal-mask compares/selects when no lane is on the diagonal tile
# speedup vs baseline: 1.0163x; 1.0163x over previous
; DI float xor32_max(float v) { const auto r = __builtin_amdgcn_permlane32_swap(__float_as_uint(v), __float_as_uint(v), false, false); return fmaxf(__uint_as_float(r[0]), __uint_as_float(r[1])); }
; DI float xor32_sum(float v) { const auto r = __builtin_amdgcn_permlane32_swap(__float_as_uint(v), __float_as_uint(v), false, false); return __uint_as_float(r[0]) + __uint_as_float(r[1]); }
; DI int crow(int i, int hh) { return (i & 3) + 8 * (i >> 2) + 4 * hh; }
; DI void attn_task(const Params& P, int bh, int n, int t, int lane, const char* Ks, const char* Vs) {
;     ...
;   for (int kt = 0; kt < nkt; ++kt) {
;     const int kbase = n * 256 + kt * 32;
;     const int krow = kt * 32 + r;
;     f32x16 S;
; #pragma unroll
;     for (int i = 0; i < 16; ++i) S[i] = 0.f;
; #pragma unroll
;     for (int s = 0; s < 4; ++s) {
;       const bf16x8 kf = *reinterpret_cast<const bf16x8*>(Ks + krow * 128 + (((2 * s + hh) ^ ((krow >> 1) & 7)) * 16));
;       S = __builtin_amdgcn_mfma_f32_32x32x16_bf16(kf, qf[s], S, 0, 0, 0);
;     }
;     const bool diag = own && (kt == t);
;     constexpr float SC2 = 0.125f * 1.4426950408889634f;
;     float mx = -1e30f;
; #pragma unroll
;     for (int i = 0; i < 16; ++i) {
;       if (diag && (kbase + crow(i, hh) > lq)) S[i] = -1e30f;
;       mx = fmaxf(mx, S[i]);
;     }
;     mx = xor32_max(mx);
;     const float m_new = fmaxf(m_run, mx * SC2);
;     const float alpha = __builtin_amdgcn_exp2f(m_run - m_new);
;     float rs = 0.f;
; #pragma unroll
;     for (int i = 0; i < 16; ++i) { float pv = __builtin_amdgcn_exp2f(fmaf(S[i], SC2, -m_new)); S[i] = pv; rs += pv; }
;     rs = xor32_sum(rs);
;     l_run = l_run * alpha + rs; m_run = m_new;
;     if (__ballot(alpha != 1.f)) {
; #pragma unroll
;       for (int i = 0; i < 16; ++i) { O0[i] *= alpha; O1[i] *= alpha; }
;     }
.LBB0_783:
	v_add_u32_e32 v0, v152, v197
	ds_read_b128 v[2:5], v0
	v_add_u32_e32 v0, v151, v197
	ds_read_b128 v[6:9], v0
	v_add_u32_e32 v10, v149, v197
	v_add_u32_e32 v11, s8, v145
	v_subrev_co_u32_e32 v144, vcc, 1, v144
	v_cmp_gt_i32_e64 s[0:1], v11, v148
	v_cmp_ge_i32_e64 s[6:7], v11, v148
	s_cbranch_vccz .Lattn_fast_783
	s_waitcnt vmcnt(3) lgkmcnt(1)
	v_mfma_f32_32x32x16_bf16 v[48:63], v[2:5], v[64:67], 0
	v_add_u32_e32 v2, v150, v197
	ds_read_b128 v[2:5], v2
	s_and_b64 s[0:1], vcc, s[0:1]
	v_add_u32_e32 v12, 3, v11
	v_add_u32_e32 v13, 8, v11
	v_cmp_gt_i32_e64 s[12:13], v12, v148
	v_add_u32_e32 v14, 9, v11
	s_waitcnt vmcnt(2) lgkmcnt(1)
	v_mfma_f32_32x32x16_bf16 v[48:63], v[6:9], v[68:71], v[48:63]
	ds_read_b128 v[6:9], v10
	v_add_u32_e32 v210, v153, v197
	v_add_u32_e32 v211, v154, v197
	ds_read2_b64 v[216:219], v210 offset1:2
	ds_read2_b64 v[220:223], v211 offset1:2
	ds_read2_b64 v[224:227], v210 offset0:4 offset1:6
	ds_read2_b64 v[228:231], v211 offset0:4 offset1:6
	v_add_u32_e32 v10, 2, v11
	v_cmp_gt_i32_e64 s[10:11], v10, v148
	v_cmp_gt_i32_e64 s[14:15], v13, v148
	v_cmp_gt_i32_e64 s[16:17], v14, v148
	v_mov_b32_e32 v0, v147
	s_waitcnt vmcnt(1) lgkmcnt(5)
	v_mfma_f32_32x32x16_bf16 v[48:63], v[2:5], v[72:75], v[48:63]
	v_add_u32_e32 v2, 10, v11
	v_cmp_gt_i32_e64 s[18:19], v2, v148
	v_add_u32_e32 v3, 11, v11
	s_waitcnt vmcnt(0) lgkmcnt(4)
	v_mfma_f32_32x32x16_bf16 v[48:63], v[6:9], v[76:79], v[48:63]
	v_add_u32_e32 v6, 16, v11
	s_nop 10
	v_cndmask_b32_e64 v2, v48, v143, s[0:1]
	s_and_b64 s[0:1], vcc, s[6:7]
	v_cndmask_b32_e64 v5, v49, v143, s[0:1]
	s_and_b64 s[0:1], vcc, s[10:11]
	v_cndmask_b32_e64 v7, v50, v143, s[0:1]
	s_and_b64 s[0:1], vcc, s[12:13]
	v_cndmask_b32_e64 v9, v51, v143, s[0:1]
	s_and_b64 s[0:1], vcc, s[14:15]
	v_cndmask_b32_e64 v10, v52, v143, s[0:1]
	s_and_b64 s[0:1], vcc, s[16:17]
	v_cndmask_b32_e64 v13, v53, v143, s[0:1]
	s_and_b64 s[0:1], vcc, s[18:19]
	v_cndmask_b32_e64 v15, v54, v143, s[0:1]
	v_cmp_gt_i32_e64 s[0:1], v3, v148
	s_and_b64 s[0:1], vcc, s[0:1]
	v_max3_f32 v4, v2, s22, v5
	v_cndmask_b32_e64 v3, v55, v143, s[0:1]
	v_cmp_gt_i32_e64 s[0:1], v6, v148
	s_and_b64 s[0:1], vcc, s[0:1]
	v_add_u32_e32 v6, 17, v11
	v_cndmask_b32_e64 v50, v56, v143, s[0:1]
	v_cmp_gt_i32_e64 s[0:1], v6, v148
	s_and_b64 s[0:1], vcc, s[0:1]
	v_add_u32_e32 v6, 18, v11
	v_cndmask_b32_e64 v51, v57, v143, s[0:1]
	v_cmp_gt_i32_e64 s[0:1], v6, v148
	s_and_b64 s[0:1], vcc, s[0:1]
	v_add_u32_e32 v6, 19, v11
	v_cndmask_b32_e64 v52, v58, v143, s[0:1]
	v_cmp_gt_i32_e64 s[0:1], v6, v148
	s_and_b64 s[0:1], vcc, s[0:1]
	v_add_u32_e32 v6, 24, v11
	v_cndmask_b32_e64 v53, v59, v143, s[0:1]
	v_cmp_gt_i32_e64 s[0:1], v6, v148
	s_and_b64 s[0:1], vcc, s[0:1]
	v_add_u32_e32 v6, 25, v11
	v_cndmask_b32_e64 v54, v60, v143, s[0:1]
	v_cmp_gt_i32_e64 s[0:1], v6, v148
	v_max3_f32 v4, v4, v7, v9
	s_and_b64 s[0:1], vcc, s[0:1]
	v_add_u32_e32 v6, 26, v11
	v_max3_f32 v4, v4, v10, v13
	v_cndmask_b32_e64 v55, v61, v143, s[0:1]
	v_cmp_gt_i32_e64 s[0:1], v6, v148
	v_max3_f32 v4, v4, v15, v3
	s_and_b64 s[0:1], vcc, s[0:1]
	v_add_u32_e32 v6, 27, v11
	v_max3_f32 v4, v4, v50, v51
	v_cndmask_b32_e64 v56, v62, v143, s[0:1]
	v_cmp_gt_i32_e64 s[0:1], v6, v148
	v_max3_f32 v4, v4, v52, v53
	s_and_b64 vcc, vcc, s[0:1]
	v_max3_f32 v4, v4, v54, v55
	v_cndmask_b32_e32 v57, v63, v143, vcc
	v_max3_f32 v4, v4, v56, v57
.Lattn_join_783:
	v_mov_b32_e32 v6, v4
	s_nop 1
	v_permlane32_swap_b32_e32 v4, v6
	v_max_f32_e32 v6, v6, v6
	v_max_f32_e32 v4, v4, v4
	v_max_f32_e32 v4, v4, v6
	v_mul_f32_e32 v4, 0x3e38aa3b, v4
	v_max_f32_e32 v6, v0, v0
	v_max_f32_e32 v147, v6, v4
	v_fma_f32 v2, v2, s23, -v147
	v_exp_f32_e32 v4, v2
	v_fma_f32 v2, v5, s23, -v147
	v_exp_f32_e32 v6, v2
	v_fma_f32 v2, v7, s23, -v147
	v_exp_f32_e32 v8, v2
	v_fma_f32 v2, v9, s23, -v147
	v_exp_f32_e32 v9, v2
	v_fma_f32 v5, v10, s23, -v147
	v_add_f32_e32 v2, 0, v4
	v_exp_f32_e32 v12, v5
	v_fma_f32 v5, v13, s23, -v147
	v_add_f32_e32 v2, v6, v2
	v_exp_f32_e32 v14, v5
	v_fma_f32 v5, v15, s23, -v147
	v_add_f32_e32 v2, v8, v2
	v_exp_f32_e32 v48, v5
	v_fma_f32 v3, v3, s23, -v147
	v_add_f32_e32 v2, v9, v2
	v_exp_f32_e32 v49, v3
	v_add_f32_e32 v2, v12, v2
	v_add_f32_e32 v2, v14, v2
	v_add_f32_e32 v2, v48, v2
	v_add_f32_e32 v10, v49, v2
	v_fma_f32 v2, v50, s23, -v147
	v_exp_f32_e32 v2, v2
	v_fma_f32 v3, v51, s23, -v147
	v_exp_f32_e32 v3, v3
	v_fma_f32 v5, v52, s23, -v147
	v_exp_f32_e32 v5, v5
	v_fma_f32 v7, v53, s23, -v147
	v_exp_f32_e32 v7, v7
	v_add_f32_e32 v10, v2, v10
	v_add_f32_e32 v10, v3, v10
	v_add_f32_e32 v10, v5, v10
	v_add_f32_e32 v50, v7, v10
	v_fma_f32 v10, v54, s23, -v147
	v_exp_f32_e32 v10, v10
	v_fma_f32 v11, v55, s23, -v147
	v_exp_f32_e32 v11, v11
	v_fma_f32 v13, v56, s23, -v147
	v_exp_f32_e32 v13, v13
	v_fma_f32 v15, v57, s23, -v147
	v_exp_f32_e32 v15, v15
	v_sub_f32_e32 v0, v0, v147
	v_add_f32_e32 v50, v10, v50
	v_add_f32_e32 v50, v11, v50
	v_exp_f32_e32 v0, v0
	v_add_f32_e32 v50, v13, v50
	v_add_f32_e32 v50, v15, v50
	v_mov_b32_e32 v51, v50
	s_nop 1
	v_permlane32_swap_b32_e32 v50, v51
	v_cmp_neq_f32_e32 vcc, 1.0, v0
	s_cbranch_vccz .LBB0_782
	v_pk_mul_f32 v[30:31], v[30:31], v[0:1] op_sel_hi:[1,0]
	v_pk_mul_f32 v[28:29], v[28:29], v[0:1] op_sel_hi:[1,0]
	v_pk_mul_f32 v[26:27], v[26:27], v[0:1] op_sel_hi:[1,0]
	v_pk_mul_f32 v[24:25], v[24:25], v[0:1] op_sel_hi:[1,0]
	v_pk_mul_f32 v[22:23], v[22:23], v[0:1] op_sel_hi:[1,0]
	v_pk_mul_f32 v[20:21], v[20:21], v[0:1] op_sel_hi:[1,0]
	v_pk_mul_f32 v[18:19], v[18:19], v[0:1] op_sel_hi:[1,0]
	v_pk_mul_f32 v[16:17], v[16:17], v[0:1] op_sel_hi:[1,0]
	v_pk_mul_f32 v[46:47], v[46:47], v[0:1] op_sel_hi:[1,0]
	v_pk_mul_f32 v[44:45], v[44:45], v[0:1] op_sel_hi:[1,0]
	v_pk_mul_f32 v[42:43], v[42:43], v[0:1] op_sel_hi:[1,0]
	v_pk_mul_f32 v[40:41], v[40:41], v[0:1] op_sel_hi:[1,0]
	v_pk_mul_f32 v[38:39], v[38:39], v[0:1] op_sel_hi:[1,0]
	v_pk_mul_f32 v[36:37], v[36:37], v[0:1] op_sel_hi:[1,0]
	v_pk_mul_f32 v[34:35], v[34:35], v[0:1] op_sel_hi:[1,0]
	v_pk_mul_f32 v[32:33], v[32:33], v[0:1] op_sel_hi:[1,0]
	s_branch .LBB0_782

; DI float xor32_max(float v) { const auto r = __builtin_amdgcn_permlane32_swap(__float_as_uint(v), __float_as_uint(v), false, false); return fmaxf(__uint_as_float(r[0]), __uint_as_float(r[1])); }
; DI float xor32_sum(float v) { const auto r = __builtin_amdgcn_permlane32_swap(__float_as_uint(v), __float_as_uint(v), false, false); return __uint_as_float(r[0]) + __uint_as_float(r[1]); }
; DI int crow(int i, int hh) { return (i & 3) + 8 * (i >> 2) + 4 * hh; }
; DI void attn_task(const Params& P, int bh, int n, int t, int lane, const char* Ks, const char* Vs) {
;     ...
;   for (int kt = 0; kt < nkt; ++kt) {
;     const int kbase = n * 256 + kt * 32;
;     const int krow = kt * 32 + r;
;     f32x16 S;
; #pragma unroll
;     for (int i = 0; i < 16; ++i) S[i] = 0.f;
; #pragma unroll
;     for (int s = 0; s < 4; ++s) {
;       const bf16x8 kf = *reinterpret_cast<const bf16x8*>(Ks + krow * 128 + (((2 * s + hh) ^ ((krow >> 1) & 7)) * 16));
;       S = __builtin_amdgcn_mfma_f32_32x32x16_bf16(kf, qf[s], S, 0, 0, 0);
;     }
;     const bool diag = own && (kt == t);
;     constexpr float SC2 = 0.125f * 1.4426950408889634f;
;     float mx = -1e30f;
; #pragma unroll
;     for (int i = 0; i < 16; ++i) {
;       if (diag && (kbase + crow(i, hh) > lq)) S[i] = -1e30f;
;       mx = fmaxf(mx, S[i]);
;     }
;     mx = xor32_max(mx);
;     const float m_new = fmaxf(m_run, mx * SC2);
;     const float alpha = __builtin_amdgcn_exp2f(m_run - m_new);
;     float rs = 0.f;
; #pragma unroll
;     for (int i = 0; i < 16; ++i) { float pv = __builtin_amdgcn_exp2f(fmaf(S[i], SC2, -m_new)); S[i] = pv; rs += pv; }
;     rs = xor32_sum(rs);
;     l_run = l_run * alpha + rs; m_run = m_new;
;     if (__ballot(alpha != 1.f)) {
; #pragma unroll
;       for (int i = 0; i < 16; ++i) { O0[i] *= alpha; O1[i] *= alpha; }
;     }
.LBB0_790:
	v_add_u32_e32 v0, v148, v197
	ds_read_b128 v[34:37], v0
	v_add_u32_e32 v0, v147, v197
	ds_read_b128 v[152:155], v0
	v_mov_b32_e32 v0, v71
	v_add_u32_e32 v71, v91, v197
	ds_read_b128 v[156:159], v71
	v_add_u32_e32 v160, v90, v197
	v_add_u32_e32 v161, s8, v89
	v_subrev_co_u32_e32 v88, vcc, 1, v88
	s_cbranch_vccz .Lattn_fast_790
	s_waitcnt vmcnt(3) lgkmcnt(2)
	v_mfma_f32_32x32x16_bf16 v[34:49], v[34:37], v[50:53], 0
	v_cmp_gt_i32_e64 s[0:1], v161, v78
	v_cmp_ge_i32_e64 s[10:11], v161, v78
	v_add_u32_e32 v71, 2, v161
	s_and_b64 s[0:1], vcc, s[0:1]
	v_cmp_gt_i32_e64 s[12:13], v71, v78
	v_add_u32_e32 v163, 8, v161
	v_add_u32_e32 v164, 9, v161
	s_waitcnt vmcnt(2) lgkmcnt(1)
	v_mfma_f32_32x32x16_bf16 v[34:49], v[152:155], v[54:57], v[34:49]
	ds_read_b128 v[152:155], v160
	v_add_u32_e32 v210, v149, v197
	v_add_u32_e32 v211, v150, v197
	ds_read2_b64 v[216:219], v210 offset1:2
	ds_read2_b64 v[220:223], v211 offset1:2
	ds_read2_b64 v[224:227], v210 offset0:4 offset1:6
	ds_read2_b64 v[228:231], v211 offset0:4 offset1:6
	v_add_u32_e32 v160, 3, v161
	v_cmp_gt_i32_e64 s[14:15], v160, v78
	v_cmp_gt_i32_e64 s[16:17], v163, v78
	v_cmp_gt_i32_e64 s[18:19], v164, v78
	s_waitcnt vmcnt(1) lgkmcnt(5)
	v_mfma_f32_32x32x16_bf16 v[34:49], v[156:159], v[58:61], v[34:49]
	v_add_u32_e32 v156, 10, v161
	v_cmp_gt_i32_e64 s[20:21], v156, v78
	v_add_u32_e32 v157, 11, v161
	s_waitcnt vmcnt(0) lgkmcnt(4)
	v_mfma_f32_32x32x16_bf16 v[34:49], v[152:155], v[62:65], v[34:49]
	s_nop 11
	v_cndmask_b32_e64 v34, v34, v143, s[0:1]
	s_and_b64 s[0:1], vcc, s[10:11]
	v_cndmask_b32_e64 v152, v35, v143, s[0:1]
	s_and_b64 s[0:1], vcc, s[12:13]
	v_cndmask_b32_e64 v153, v36, v143, s[0:1]
	s_and_b64 s[0:1], vcc, s[14:15]
	v_cndmask_b32_e64 v37, v37, v143, s[0:1]
	s_and_b64 s[0:1], vcc, s[16:17]
	v_cndmask_b32_e64 v38, v38, v143, s[0:1]
	s_and_b64 s[0:1], vcc, s[18:19]
	v_cndmask_b32_e64 v154, v39, v143, s[0:1]
	s_and_b64 s[0:1], vcc, s[20:21]
	v_cndmask_b32_e64 v40, v40, v143, s[0:1]
	v_cmp_gt_i32_e64 s[0:1], v157, v78
	s_and_b64 s[0:1], vcc, s[0:1]
	v_add_u32_e32 v36, 16, v161
	v_cndmask_b32_e64 v155, v41, v143, s[0:1]
	v_cmp_gt_i32_e64 s[0:1], v36, v78
	s_and_b64 s[0:1], vcc, s[0:1]
	v_add_u32_e32 v36, 17, v161
	v_cndmask_b32_e64 v42, v42, v143, s[0:1]
	v_cmp_gt_i32_e64 s[0:1], v36, v78
	s_and_b64 s[0:1], vcc, s[0:1]
	v_add_u32_e32 v36, 18, v161
	v_cndmask_b32_e64 v156, v43, v143, s[0:1]
	v_cmp_gt_i32_e64 s[0:1], v36, v78
	s_and_b64 s[0:1], vcc, s[0:1]
	v_add_u32_e32 v36, 19, v161
	v_cndmask_b32_e64 v44, v44, v143, s[0:1]
	v_cmp_gt_i32_e64 s[0:1], v36, v78
	s_and_b64 s[0:1], vcc, s[0:1]
	v_add_u32_e32 v36, 24, v161
	v_cndmask_b32_e64 v157, v45, v143, s[0:1]
	v_cmp_gt_i32_e64 s[0:1], v36, v78
	s_and_b64 s[0:1], vcc, s[0:1]
	v_add_u32_e32 v36, 25, v161
	v_max3_f32 v35, v34, s22, v152
	v_cndmask_b32_e64 v46, v46, v143, s[0:1]
	v_cmp_gt_i32_e64 s[0:1], v36, v78
	v_max3_f32 v35, v35, v153, v37
	s_and_b64 s[0:1], vcc, s[0:1]
	v_add_u32_e32 v36, 26, v161
	v_max3_f32 v35, v35, v38, v154
	v_cndmask_b32_e64 v158, v47, v143, s[0:1]
	v_cmp_gt_i32_e64 s[0:1], v36, v78
	v_max3_f32 v35, v35, v40, v155
	s_and_b64 s[0:1], vcc, s[0:1]
	v_add_u32_e32 v36, 27, v161
	v_max3_f32 v35, v35, v42, v156
	v_cndmask_b32_e64 v48, v48, v143, s[0:1]
	v_cmp_gt_i32_e64 s[0:1], v36, v78
	v_max3_f32 v35, v35, v44, v157
	s_and_b64 vcc, vcc, s[0:1]
	v_max3_f32 v35, v35, v46, v158
	v_cndmask_b32_e32 v159, v49, v143, vcc
	v_max3_f32 v35, v35, v48, v159
.Lattn_join_790:
	v_mov_b32_e32 v36, v35
	s_nop 1
	v_permlane32_swap_b32_e32 v35, v36
	v_max_f32_e32 v36, v36, v36
	v_max_f32_e32 v35, v35, v35
	v_max_f32_e32 v35, v35, v36
	v_mul_f32_e32 v35, 0x3e38aa3b, v35
	v_max_f32_e32 v36, v0, v0
	v_max_f32_e32 v71, v36, v35
	v_fma_f32 v34, v34, s23, -v71
	v_exp_f32_e32 v35, v34
	v_fma_f32 v34, v152, s23, -v71
	v_exp_f32_e32 v36, v34
	v_fma_f32 v34, v153, s23, -v71
	v_exp_f32_e32 v39, v34
	v_fma_f32 v34, v37, s23, -v71
	v_exp_f32_e32 v41, v34
	v_fma_f32 v37, v38, s23, -v71
	v_add_f32_e32 v34, 0, v35
	v_exp_f32_e32 v43, v37
	v_fma_f32 v37, v154, s23, -v71
	v_add_f32_e32 v34, v36, v34
	v_exp_f32_e32 v45, v37
	v_fma_f32 v37, v40, s23, -v71
	v_add_f32_e32 v34, v39, v34
	v_exp_f32_e32 v47, v37
	v_fma_f32 v37, v155, s23, -v71
	v_add_f32_e32 v34, v41, v34
	v_exp_f32_e32 v49, v37
	v_add_f32_e32 v34, v43, v34
	v_add_f32_e32 v34, v45, v34
	v_add_f32_e32 v34, v47, v34
	v_add_f32_e32 v152, v49, v34
	v_fma_f32 v34, v42, s23, -v71
	v_exp_f32_e32 v34, v34
	v_fma_f32 v37, v156, s23, -v71
	v_exp_f32_e32 v37, v37
	v_fma_f32 v38, v44, s23, -v71
	v_exp_f32_e32 v38, v38
	v_fma_f32 v40, v157, s23, -v71
	v_exp_f32_e32 v40, v40
	v_add_f32_e32 v42, v34, v152
	v_add_f32_e32 v42, v37, v42
	v_add_f32_e32 v42, v38, v42
	v_add_f32_e32 v152, v40, v42
	v_fma_f32 v42, v46, s23, -v71
	v_exp_f32_e32 v42, v42
	v_fma_f32 v44, v158, s23, -v71
	v_exp_f32_e32 v44, v44
	v_fma_f32 v46, v48, s23, -v71
	v_exp_f32_e32 v46, v46
	v_fma_f32 v48, v159, s23, -v71
	v_exp_f32_e32 v48, v48
	v_sub_f32_e32 v0, v0, v71
	v_add_f32_e32 v152, v42, v152
	v_add_f32_e32 v152, v44, v152
	v_exp_f32_e32 v0, v0
	v_add_f32_e32 v152, v46, v152
	v_add_f32_e32 v152, v48, v152
	v_mov_b32_e32 v153, v152
	s_nop 1
	v_permlane32_swap_b32_e32 v152, v153
	v_cmp_neq_f32_e32 vcc, 1.0, v0
	s_cbranch_vccz .LBB0_792
	v_pk_mul_f32 v[32:33], v[32:33], v[0:1] op_sel_hi:[1,0]
	v_pk_mul_f32 v[30:31], v[30:31], v[0:1] op_sel_hi:[1,0]
	v_pk_mul_f32 v[28:29], v[28:29], v[0:1] op_sel_hi:[1,0]
	v_pk_mul_f32 v[26:27], v[26:27], v[0:1] op_sel_hi:[1,0]
	v_pk_mul_f32 v[24:25], v[24:25], v[0:1] op_sel_hi:[1,0]
	v_pk_mul_f32 v[22:23], v[22:23], v[0:1] op_sel_hi:[1,0]
	v_pk_mul_f32 v[20:21], v[20:21], v[0:1] op_sel_hi:[1,0]
	v_pk_mul_f32 v[18:19], v[18:19], v[0:1] op_sel_hi:[1,0]
	v_pk_mul_f32 v[16:17], v[16:17], v[0:1] op_sel_hi:[1,0]
	v_pk_mul_f32 v[14:15], v[14:15], v[0:1] op_sel_hi:[1,0]
	v_pk_mul_f32 v[12:13], v[12:13], v[0:1] op_sel_hi:[1,0]
	v_pk_mul_f32 v[10:11], v[10:11], v[0:1] op_sel_hi:[1,0]
	v_pk_mul_f32 v[8:9], v[8:9], v[0:1] op_sel_hi:[1,0]
	v_pk_mul_f32 v[6:7], v[6:7], v[0:1] op_sel_hi:[1,0]
	v_pk_mul_f32 v[4:5], v[4:5], v[0:1] op_sel_hi:[1,0]
	v_pk_mul_f32 v[2:3], v[2:3], v[0:1] op_sel_hi:[1,0]

; DI int crow(int i, int hh) { return (i & 3) + 8 * (i >> 2) + 4 * hh; }
; DI void attn_task(const Params& P, int bh, int n, int t, int lane, const char* Ks, const char* Vs) {
;     ...
; #pragma unroll
;     for (int s = 0; s < 4; ++s) {
;       const bf16x8 kf = *reinterpret_cast<const bf16x8*>(Ks + krow * 128 + (((2 * s + hh) ^ ((krow >> 1) & 7)) * 16));
;       S = __builtin_amdgcn_mfma_f32_32x32x16_bf16(kf, qf[s], S, 0, 0, 0);
;     }
;     const bool diag = own && (kt == t);
;     constexpr float SC2 = 0.125f * 1.4426950408889634f;
;     float mx = -1e30f;
; #pragma unroll
;     for (int i = 0; i < 16; ++i) {
;       if (diag && (kbase + crow(i, hh) > lq)) S[i] = -1e30f;
;       mx = fmaxf(mx, S[i]);
;     }
.Lattn_fast_783:
	s_waitcnt vmcnt(3) lgkmcnt(1)
	v_mfma_f32_32x32x16_bf16 v[48:63], v[2:5], v[64:67], 0
	v_add_u32_e32 v2, v150, v197
	ds_read_b128 v[2:5], v2
	s_waitcnt vmcnt(2) lgkmcnt(1)
	v_mfma_f32_32x32x16_bf16 v[48:63], v[6:9], v[68:71], v[48:63]
	ds_read_b128 v[6:9], v10
	v_add_u32_e32 v210, v153, v197
	v_add_u32_e32 v211, v154, v197
	ds_read2_b64 v[216:219], v210 offset1:2
	ds_read2_b64 v[220:223], v211 offset1:2
	ds_read2_b64 v[224:227], v210 offset0:4 offset1:6
	ds_read2_b64 v[228:231], v211 offset0:4 offset1:6
	v_mov_b32_e32 v0, v147
	s_waitcnt vmcnt(1) lgkmcnt(5)
	v_mfma_f32_32x32x16_bf16 v[48:63], v[2:5], v[72:75], v[48:63]
	s_waitcnt vmcnt(0) lgkmcnt(4)
	v_mfma_f32_32x32x16_bf16 v[48:63], v[6:9], v[76:79], v[48:63]
	s_nop 11
	v_mov_b32_e32 v2, v48
	v_mov_b32_e32 v5, v49
	v_mov_b32_e32 v7, v50
	v_mov_b32_e32 v9, v51
	v_mov_b32_e32 v10, v52
	v_mov_b32_e32 v13, v53
	v_mov_b32_e32 v15, v54
	v_mov_b32_e32 v3, v55
	v_mov_b32_e32 v50, v56
	v_mov_b32_e32 v51, v57
	v_mov_b32_e32 v52, v58
	v_mov_b32_e32 v53, v59
	v_mov_b32_e32 v54, v60
	v_mov_b32_e32 v55, v61
	v_mov_b32_e32 v56, v62
	v_mov_b32_e32 v57, v63
	v_max3_f32 v4, v2, s22, v5
	v_max3_f32 v4, v4, v7, v9
	v_max3_f32 v4, v4, v10, v13
	v_max3_f32 v4, v4, v15, v3
	v_max3_f32 v4, v4, v50, v51
	v_max3_f32 v4, v4, v52, v53
	v_max3_f32 v4, v4, v54, v55
	v_max3_f32 v4, v4, v56, v57
	s_branch .Lattn_join_783
.Lattn_fast_790:
	s_waitcnt vmcnt(3) lgkmcnt(2)
	v_mfma_f32_32x32x16_bf16 v[34:49], v[34:37], v[50:53], 0
	s_waitcnt vmcnt(2) lgkmcnt(1)
	v_mfma_f32_32x32x16_bf16 v[34:49], v[152:155], v[54:57], v[34:49]
	ds_read_b128 v[152:155], v160
	v_add_u32_e32 v210, v149, v197
	v_add_u32_e32 v211, v150, v197
	ds_read2_b64 v[216:219], v210 offset1:2
	ds_read2_b64 v[220:223], v211 offset1:2
	ds_read2_b64 v[224:227], v210 offset0:4 offset1:6
	ds_read2_b64 v[228:231], v211 offset0:4 offset1:6
	s_waitcnt vmcnt(1) lgkmcnt(5)
	v_mfma_f32_32x32x16_bf16 v[34:49], v[156:159], v[58:61], v[34:49]
	s_waitcnt vmcnt(0) lgkmcnt(4)
	v_mfma_f32_32x32x16_bf16 v[34:49], v[152:155], v[62:65], v[34:49]
	s_nop 11
	v_mov_b32_e32 v152, v35
	v_mov_b32_e32 v153, v36
	v_mov_b32_e32 v154, v39
	v_mov_b32_e32 v155, v41
	v_mov_b32_e32 v156, v43
	v_mov_b32_e32 v157, v45
	v_mov_b32_e32 v158, v47
	v_mov_b32_e32 v159, v49
	v_max3_f32 v35, v34, s22, v152
	v_max3_f32 v35, v35, v153, v37
	v_max3_f32 v35, v35, v38, v154
	v_max3_f32 v35, v35, v40, v155
	v_max3_f32 v35, v35, v42, v156
	v_max3_f32 v35, v35, v44, v157
	v_max3_f32 v35, v35, v46, v158
	v_max3_f32 v35, v35, v48, v159
	s_branch .Lattn_join_790
.Lattn_fast_804:
	s_waitcnt vmcnt(3) lgkmcnt(2)
	v_mfma_f32_32x32x16_bf16 v[34:49], v[34:37], v[50:53], 0
	s_waitcnt vmcnt(2) lgkmcnt(1)
	v_mfma_f32_32x32x16_bf16 v[34:49], v[152:155], v[54:57], v[34:49]
	ds_read_b128 v[152:155], v161
	v_add_u32_e32 v210, v149, v197
	v_add_u32_e32 v211, v150, v197
	ds_read2_b64 v[216:219], v210 offset1:2
	ds_read2_b64 v[220:223], v211 offset1:2
	ds_read2_b64 v[224:227], v210 offset0:4 offset1:6
	ds_read2_b64 v[228:231], v211 offset0:4 offset1:6
	s_waitcnt vmcnt(1) lgkmcnt(5)
	v_mfma_f32_32x32x16_bf16 v[34:49], v[156:159], v[58:61], v[34:49]
	s_waitcnt vmcnt(0) lgkmcnt(4)
	v_mfma_f32_32x32x16_bf16 v[34:49], v[152:155], v[62:65], v[34:49]
	s_nop 11
	v_mov_b32_e32 v152, v36
	v_mov_b32_e32 v153, v39
	v_mov_b32_e32 v154, v40
	v_mov_b32_e32 v155, v42
	v_mov_b32_e32 v156, v44
	v_mov_b32_e32 v157, v47
	v_mov_b32_e32 v158, v48
	v_max3_f32 v36, v34, s22, v35
	v_max3_f32 v36, v36, v152, v37
	v_max3_f32 v36, v36, v38, v153
	v_max3_f32 v36, v36, v154, v41
	v_max3_f32 v36, v36, v155, v43
	v_max3_f32 v36, v36, v156, v45
	v_max3_f32 v36, v36, v46, v157
	v_max3_f32 v36, v36, v158, v49
	s_branch .Lattn_join_804
.Lattn_fast_815:
	s_waitcnt vmcnt(3) lgkmcnt(2)
	v_mfma_f32_32x32x16_bf16 v[34:49], v[34:37], v[50:53], 0
	s_waitcnt vmcnt(2) lgkmcnt(1)
	v_mfma_f32_32x32x16_bf16 v[34:49], v[154:157], v[54:57], v[34:49]
	ds_read_b128 v[154:157], v153
	v_add_u32_e32 v210, v150, v197
	v_add_u32_e32 v211, v151, v197
	ds_read2_b64 v[216:219], v210 offset1:2
	ds_read2_b64 v[220:223], v211 offset1:2
	ds_read2_b64 v[224:227], v210 offset0:4 offset1:6
	ds_read2_b64 v[228:231], v211 offset0:4 offset1:6
	s_waitcnt vmcnt(1) lgkmcnt(5)
	v_mfma_f32_32x32x16_bf16 v[34:49], v[158:161], v[58:61], v[34:49]
	s_waitcnt vmcnt(0) lgkmcnt(4)
	v_mfma_f32_32x32x16_bf16 v[34:49], v[154:157], v[62:65], v[34:49]
	s_nop 11
	v_mov_b32_e32 v153, v36
	v_mov_b32_e32 v154, v38
	v_mov_b32_e32 v155, v40
	v_mov_b32_e32 v156, v41
	v_mov_b32_e32 v157, v44
	v_mov_b32_e32 v158, v46
	v_mov_b32_e32 v159, v48
	v_mov_b32_e32 v160, v49
	v_max3_f32 v36, v34, s22, v35
	v_max3_f32 v36, v36, v153, v37
	v_max3_f32 v36, v36, v154, v39
	v_max3_f32 v36, v36, v155, v156
	v_max3_f32 v36, v36, v42, v43
	v_max3_f32 v36, v36, v157, v45
	v_max3_f32 v36, v36, v158, v47
	v_max3_f32 v36, v36, v159, v160
	s_branch .Lattn_join_815

; DI float xor32_max(float v) { const auto r = __builtin_amdgcn_permlane32_swap(__float_as_uint(v), __float_as_uint(v), false, false); return fmaxf(__uint_as_float(r[0]), __uint_as_float(r[1])); }
; DI float xor32_sum(float v) { const auto r = __builtin_amdgcn_permlane32_swap(__float_as_uint(v), __float_as_uint(v), false, false); return __uint_as_float(r[0]) + __uint_as_float(r[1]); }
; DI int crow(int i, int hh) { return (i & 3) + 8 * (i >> 2) + 4 * hh; }
; DI void attn_task(const Params& P, int bh, int n, int t, int lane, const char* Ks, const char* Vs) {
;     ...
;   for (int kt = 0; kt < nkt; ++kt) {
;     const int kbase = n * 256 + kt * 32;
;     const int krow = kt * 32 + r;
;     f32x16 S;
; #pragma unroll
;     for (int i = 0; i < 16; ++i) S[i] = 0.f;
; #pragma unroll
;     for (int s = 0; s < 4; ++s) {
;       const bf16x8 kf = *reinterpret_cast<const bf16x8*>(Ks + krow * 128 + (((2 * s + hh) ^ ((krow >> 1) & 7)) * 16));
;       S = __builtin_amdgcn_mfma_f32_32x32x16_bf16(kf, qf[s], S, 0, 0, 0);
;     }
;     const bool diag = own && (kt == t);
;     constexpr float SC2 = 0.125f * 1.4426950408889634f;
;     float mx = -1e30f;
; #pragma unroll
;     for (int i = 0; i < 16; ++i) {
;       if (diag && (kbase + crow(i, hh) > lq)) S[i] = -1e30f;
;       mx = fmaxf(mx, S[i]);
;     }
;     mx = xor32_max(mx);
;     const float m_new = fmaxf(m_run, mx * SC2);
;     const float alpha = __builtin_amdgcn_exp2f(m_run - m_new);
;     float rs = 0.f;
; #pragma unroll
;     for (int i = 0; i < 16; ++i) { float pv = __builtin_amdgcn_exp2f(fmaf(S[i], SC2, -m_new)); S[i] = pv; rs += pv; }
;     rs = xor32_sum(rs);
;     l_run = l_run * alpha + rs; m_run = m_new;
;     if (__ballot(alpha != 1.f)) {
; #pragma unroll
;       for (int i = 0; i < 16; ++i) { O0[i] *= alpha; O1[i] *= alpha; }
;     }
.LBB0_804:
	v_add_u32_e32 v34, v148, v197
	ds_read_b128 v[34:37], v34
	v_add_u32_e32 v38, v147, v197
	ds_read_b128 v[152:155], v38
	v_mov_b32_e32 v160, v79
	v_add_u32_e32 v79, v91, v197
	ds_read_b128 v[156:159], v79
	v_add_u32_e32 v161, v90, v197
	v_subrev_u32_e32 v163, 27, v89
	v_cmp_eq_u32_e32 vcc, 1, v88
	s_cbranch_vccz .Lattn_fast_804
	s_waitcnt vmcnt(3) lgkmcnt(2)
	v_mfma_f32_32x32x16_bf16 v[34:49], v[34:37], v[50:53], 0
	v_cmp_gt_i32_e64 s[0:1], v163, v78
	v_subrev_u32_e32 v164, 25, v89
	v_cmp_ge_i32_e64 s[10:11], v163, v78
	s_and_b64 s[0:1], vcc, s[0:1]
	v_subrev_u32_e32 v79, 24, v89
	v_cmp_gt_i32_e64 s[12:13], v164, v78
	v_subrev_u32_e32 v165, 19, v89
	s_waitcnt vmcnt(2) lgkmcnt(1)
	v_mfma_f32_32x32x16_bf16 v[34:49], v[152:155], v[54:57], v[34:49]
	ds_read_b128 v[152:155], v161
	v_add_u32_e32 v210, v149, v197
	v_add_u32_e32 v211, v150, v197
	ds_read2_b64 v[216:219], v210 offset1:2
	ds_read2_b64 v[220:223], v211 offset1:2
	ds_read2_b64 v[224:227], v210 offset0:4 offset1:6
	ds_read2_b64 v[228:231], v211 offset0:4 offset1:6
	v_cmp_gt_i32_e64 s[14:15], v79, v78
	v_subrev_u32_e32 v166, 18, v89
	v_cmp_gt_i32_e64 s[16:17], v165, v78
	v_subrev_u32_e32 v167, 17, v89
	v_cmp_gt_i32_e64 s[18:19], v166, v78
	v_add_u32_e32 v172, -16, v89
	s_waitcnt vmcnt(1) lgkmcnt(5)
	v_mfma_f32_32x32x16_bf16 v[34:49], v[156:159], v[58:61], v[34:49]
	v_cmp_gt_i32_e64 s[20:21], v167, v78
	v_cmp_gt_i32_e64 s[24:25], v172, v78
	s_waitcnt vmcnt(0) lgkmcnt(4)
	v_mfma_f32_32x32x16_bf16 v[34:49], v[152:155], v[62:65], v[34:49]
	s_nop 11
	v_cndmask_b32_e64 v34, v34, v143, s[0:1]
	s_and_b64 s[0:1], vcc, s[10:11]
	v_cndmask_b32_e64 v35, v35, v143, s[0:1]
	s_and_b64 s[0:1], vcc, s[12:13]
	v_cndmask_b32_e64 v152, v36, v143, s[0:1]
	s_and_b64 s[0:1], vcc, s[14:15]
	v_cndmask_b32_e64 v37, v37, v143, s[0:1]
	s_and_b64 s[0:1], vcc, s[16:17]
	v_cndmask_b32_e64 v38, v38, v143, s[0:1]
	s_and_b64 s[0:1], vcc, s[18:19]
	v_cndmask_b32_e64 v153, v39, v143, s[0:1]
	s_and_b64 s[0:1], vcc, s[20:21]
	v_cndmask_b32_e64 v154, v40, v143, s[0:1]
	s_and_b64 s[0:1], vcc, s[24:25]
	v_add_u32_e32 v39, -11, v89
	v_cndmask_b32_e64 v41, v41, v143, s[0:1]
	v_cmp_gt_i32_e64 s[0:1], v39, v78
	s_and_b64 s[0:1], vcc, s[0:1]
	v_add_u32_e32 v39, -10, v89
	v_cndmask_b32_e64 v155, v42, v143, s[0:1]
	v_cmp_gt_i32_e64 s[0:1], v39, v78
	s_and_b64 s[0:1], vcc, s[0:1]
	v_add_u32_e32 v39, -9, v89
	v_cndmask_b32_e64 v43, v43, v143, s[0:1]
	v_cmp_gt_i32_e64 s[0:1], v39, v78
	s_and_b64 s[0:1], vcc, s[0:1]
	v_add_u32_e32 v39, -8, v89
	v_cndmask_b32_e64 v156, v44, v143, s[0:1]
	v_cmp_gt_i32_e64 s[0:1], v39, v78
	s_and_b64 s[0:1], vcc, s[0:1]
	v_add_u32_e32 v39, -3, v89
	v_cndmask_b32_e64 v45, v45, v143, s[0:1]
	v_cmp_gt_i32_e64 s[0:1], v39, v78
	s_and_b64 s[0:1], vcc, s[0:1]
	v_add_u32_e32 v39, -2, v89
	v_max3_f32 v36, v34, s22, v35
	v_cndmask_b32_e64 v46, v46, v143, s[0:1]
	v_cmp_gt_i32_e64 s[0:1], v39, v78
	v_max3_f32 v36, v36, v152, v37
	s_and_b64 s[0:1], vcc, s[0:1]
	v_add_u32_e32 v39, -1, v89
	v_max3_f32 v36, v36, v38, v153
	v_cndmask_b32_e64 v157, v47, v143, s[0:1]
	v_cmp_gt_i32_e64 s[0:1], v39, v78
	v_max3_f32 v36, v36, v154, v41
	s_and_b64 s[0:1], vcc, s[0:1]
	v_max3_f32 v36, v36, v155, v43
	v_cndmask_b32_e64 v158, v48, v143, s[0:1]
	v_cmp_gt_i32_e64 s[0:1], v89, v78
	v_max3_f32 v36, v36, v156, v45
	s_and_b64 vcc, vcc, s[0:1]
	v_max3_f32 v36, v36, v46, v157
	v_cndmask_b32_e32 v49, v49, v143, vcc
	v_max3_f32 v36, v36, v158, v49
.Lattn_join_804:
	v_mov_b32_e32 v39, v36
	s_nop 1
	v_permlane32_swap_b32_e32 v36, v39
	v_max_f32_e32 v39, v39, v39
	v_max_f32_e32 v36, v36, v36
	v_max_f32_e32 v36, v36, v39
	v_mul_f32_e32 v36, 0x3e38aa3b, v36
	v_max_f32_e32 v39, v160, v160
	v_max_f32_e32 v79, v39, v36
	v_fma_f32 v34, v34, s23, -v79
	v_exp_f32_e32 v36, v34
	v_fma_f32 v34, v35, s23, -v79
	v_exp_f32_e32 v39, v34
	v_fma_f32 v34, v152, s23, -v79
	v_exp_f32_e32 v40, v34
	v_fma_f32 v34, v37, s23, -v79
	v_exp_f32_e32 v42, v34
	v_fma_f32 v35, v38, s23, -v79
	v_add_f32_e32 v34, 0, v36
	v_exp_f32_e32 v44, v35
	v_fma_f32 v35, v153, s23, -v79
	v_add_f32_e32 v34, v39, v34
	v_exp_f32_e32 v47, v35
	v_fma_f32 v35, v154, s23, -v79
	v_add_f32_e32 v34, v40, v34
	v_exp_f32_e32 v48, v35
	v_fma_f32 v35, v41, s23, -v79
	v_add_f32_e32 v34, v42, v34
	v_exp_f32_e32 v152, v35
	v_fma_f32 v35, v155, s23, -v79
	v_add_f32_e32 v34, v44, v34
	v_exp_f32_e32 v35, v35
	v_fma_f32 v37, v43, s23, -v79
	v_add_f32_e32 v34, v47, v34
	v_exp_f32_e32 v37, v37
	v_fma_f32 v38, v156, s23, -v79
	v_add_f32_e32 v34, v48, v34
	v_exp_f32_e32 v38, v38
	v_fma_f32 v41, v45, s23, -v79
	v_add_f32_e32 v34, v152, v34
	v_exp_f32_e32 v41, v41
	v_fma_f32 v43, v46, s23, -v79
	v_add_f32_e32 v34, v35, v34
	v_exp_f32_e32 v43, v43
	v_fma_f32 v45, v157, s23, -v79
	v_add_f32_e32 v34, v37, v34
	v_exp_f32_e32 v45, v45
	v_fma_f32 v46, v158, s23, -v79
	v_add_f32_e32 v34, v38, v34
	v_exp_f32_e32 v46, v46
	v_fma_f32 v49, v49, s23, -v79
	v_add_f32_e32 v34, v41, v34
	v_exp_f32_e32 v49, v49
	v_add_f32_e32 v34, v43, v34
	v_add_f32_e32 v34, v45, v34
	v_sub_f32_e32 v159, v160, v79
	v_add_f32_e32 v34, v46, v34
	v_add_f32_e32 v153, v49, v34
	v_exp_f32_e32 v34, v159
	v_mov_b32_e32 v154, v153
	s_nop 1
	v_permlane32_swap_b32_e32 v153, v154
	v_cmp_neq_f32_e32 vcc, 1.0, v34
	s_cbranch_vccz .LBB0_803
	v_pk_mul_f32 v[16:17], v[16:17], v[34:35] op_sel_hi:[1,0]
	v_pk_mul_f32 v[14:15], v[14:15], v[34:35] op_sel_hi:[1,0]
	v_pk_mul_f32 v[12:13], v[12:13], v[34:35] op_sel_hi:[1,0]
	v_pk_mul_f32 v[10:11], v[10:11], v[34:35] op_sel_hi:[1,0]
	v_pk_mul_f32 v[8:9], v[8:9], v[34:35] op_sel_hi:[1,0]
	v_pk_mul_f32 v[6:7], v[6:7], v[34:35] op_sel_hi:[1,0]
	v_pk_mul_f32 v[4:5], v[4:5], v[34:35] op_sel_hi:[1,0]
	v_pk_mul_f32 v[2:3], v[2:3], v[34:35] op_sel_hi:[1,0]
	v_pk_mul_f32 v[32:33], v[32:33], v[34:35] op_sel_hi:[1,0]
	v_pk_mul_f32 v[30:31], v[30:31], v[34:35] op_sel_hi:[1,0]
	v_pk_mul_f32 v[28:29], v[28:29], v[34:35] op_sel_hi:[1,0]
	v_pk_mul_f32 v[26:27], v[26:27], v[34:35] op_sel_hi:[1,0]
	v_pk_mul_f32 v[24:25], v[24:25], v[34:35] op_sel_hi:[1,0]
	v_pk_mul_f32 v[22:23], v[22:23], v[34:35] op_sel_hi:[1,0]
	v_pk_mul_f32 v[20:21], v[20:21], v[34:35] op_sel_hi:[1,0]
	v_pk_mul_f32 v[18:19], v[18:19], v[34:35] op_sel_hi:[1,0]
	s_branch .LBB0_803

; DI float xor32_max(float v) { const auto r = __builtin_amdgcn_permlane32_swap(__float_as_uint(v), __float_as_uint(v), false, false); return fmaxf(__uint_as_float(r[0]), __uint_as_float(r[1])); }
; DI float xor32_sum(float v) { const auto r = __builtin_amdgcn_permlane32_swap(__float_as_uint(v), __float_as_uint(v), false, false); return __uint_as_float(r[0]) + __uint_as_float(r[1]); }
; DI int crow(int i, int hh) { return (i & 3) + 8 * (i >> 2) + 4 * hh; }
; DI void attn_task(const Params& P, int bh, int n, int t, int lane, const char* Ks, const char* Vs) {
;     ...
;   for (int kt = 0; kt < nkt; ++kt) {
;     const int kbase = n * 256 + kt * 32;
;     const int krow = kt * 32 + r;
;     f32x16 S;
; #pragma unroll
;     for (int i = 0; i < 16; ++i) S[i] = 0.f;
; #pragma unroll
;     for (int s = 0; s < 4; ++s) {
;       const bf16x8 kf = *reinterpret_cast<const bf16x8*>(Ks + krow * 128 + (((2 * s + hh) ^ ((krow >> 1) & 7)) * 16));
;       S = __builtin_amdgcn_mfma_f32_32x32x16_bf16(kf, qf[s], S, 0, 0, 0);
;     }
;     const bool diag = own && (kt == t);
;     constexpr float SC2 = 0.125f * 1.4426950408889634f;
;     float mx = -1e30f;
; #pragma unroll
;     for (int i = 0; i < 16; ++i) {
;       if (diag && (kbase + crow(i, hh) > lq)) S[i] = -1e30f;
;       mx = fmaxf(mx, S[i]);
;     }
;     mx = xor32_max(mx);
;     const float m_new = fmaxf(m_run, mx * SC2);
;     const float alpha = __builtin_amdgcn_exp2f(m_run - m_new);
;     float rs = 0.f;
; #pragma unroll
;     for (int i = 0; i < 16; ++i) { float pv = __builtin_amdgcn_exp2f(fmaf(S[i], SC2, -m_new)); S[i] = pv; rs += pv; }
;     rs = xor32_sum(rs);
;     l_run = l_run * alpha + rs; m_run = m_new;
;     if (__ballot(alpha != 1.f)) {
; #pragma unroll
;       for (int i = 0; i < 16; ++i) { O0[i] *= alpha; O1[i] *= alpha; }
;     }
.LBB0_815:
	v_add_u32_e32 v0, v149, v197
	ds_read_b128 v[34:37], v0
	v_add_u32_e32 v0, v148, v197
	ds_read_b128 v[154:157], v0
	v_mov_b32_e32 v0, v71
	v_add_u32_e32 v71, v147, v197
	ds_read_b128 v[158:161], v71
	v_add_u32_e32 v153, v91, v197
	v_add_u32_e32 v163, s8, v90
	v_subrev_co_u32_e32 v88, vcc, 1, v88
	s_cbranch_vccz .Lattn_fast_815
	s_waitcnt vmcnt(3) lgkmcnt(2)
	v_mfma_f32_32x32x16_bf16 v[34:49], v[34:37], v[50:53], 0
	v_cmp_gt_i32_e64 s[0:1], v163, v79
	v_cmp_ge_i32_e64 s[10:11], v163, v79
	v_add_u32_e32 v71, 2, v163
	s_and_b64 s[0:1], vcc, s[0:1]
	v_cmp_gt_i32_e64 s[12:13], v71, v79
	v_add_u32_e32 v164, 8, v163
	v_add_u32_e32 v165, 9, v163
	s_waitcnt vmcnt(2) lgkmcnt(1)
	v_mfma_f32_32x32x16_bf16 v[34:49], v[154:157], v[54:57], v[34:49]
	ds_read_b128 v[154:157], v153
	v_add_u32_e32 v210, v150, v197
	v_add_u32_e32 v211, v151, v197
	ds_read2_b64 v[216:219], v210 offset1:2
	ds_read2_b64 v[220:223], v211 offset1:2
	ds_read2_b64 v[224:227], v210 offset0:4 offset1:6
	ds_read2_b64 v[228:231], v211 offset0:4 offset1:6
	v_add_u32_e32 v153, 3, v163
	v_cmp_gt_i32_e64 s[14:15], v153, v79
	v_cmp_gt_i32_e64 s[16:17], v164, v79
	v_cmp_gt_i32_e64 s[18:19], v165, v79
	s_waitcnt vmcnt(1) lgkmcnt(5)
	v_mfma_f32_32x32x16_bf16 v[34:49], v[158:161], v[58:61], v[34:49]
	v_add_u32_e32 v158, 10, v163
	v_cmp_gt_i32_e64 s[20:21], v158, v79
	v_add_u32_e32 v159, 11, v163
	s_waitcnt vmcnt(0) lgkmcnt(4)
	v_mfma_f32_32x32x16_bf16 v[34:49], v[154:157], v[62:65], v[34:49]
	s_nop 11
	v_cndmask_b32_e64 v34, v34, v143, s[0:1]
	s_and_b64 s[0:1], vcc, s[10:11]
	v_cndmask_b32_e64 v35, v35, v143, s[0:1]
	s_and_b64 s[0:1], vcc, s[12:13]
	v_cndmask_b32_e64 v153, v36, v143, s[0:1]
	s_and_b64 s[0:1], vcc, s[14:15]
	v_cndmask_b32_e64 v37, v37, v143, s[0:1]
	s_and_b64 s[0:1], vcc, s[16:17]
	v_cndmask_b32_e64 v154, v38, v143, s[0:1]
	s_and_b64 s[0:1], vcc, s[18:19]
	v_cndmask_b32_e64 v39, v39, v143, s[0:1]
	s_and_b64 s[0:1], vcc, s[20:21]
	v_cndmask_b32_e64 v155, v40, v143, s[0:1]
	v_cmp_gt_i32_e64 s[0:1], v159, v79
	s_and_b64 s[0:1], vcc, s[0:1]
	v_add_u32_e32 v38, 16, v163
	v_cndmask_b32_e64 v156, v41, v143, s[0:1]
	v_cmp_gt_i32_e64 s[0:1], v38, v79
	s_and_b64 s[0:1], vcc, s[0:1]
	v_add_u32_e32 v38, 17, v163
	v_cndmask_b32_e64 v42, v42, v143, s[0:1]
	v_cmp_gt_i32_e64 s[0:1], v38, v79
	s_and_b64 s[0:1], vcc, s[0:1]
	v_add_u32_e32 v38, 18, v163
	v_cndmask_b32_e64 v43, v43, v143, s[0:1]
	v_cmp_gt_i32_e64 s[0:1], v38, v79
	s_and_b64 s[0:1], vcc, s[0:1]
	v_add_u32_e32 v38, 19, v163
	v_cndmask_b32_e64 v157, v44, v143, s[0:1]
	v_cmp_gt_i32_e64 s[0:1], v38, v79
	s_and_b64 s[0:1], vcc, s[0:1]
	v_add_u32_e32 v38, 24, v163
	v_cndmask_b32_e64 v45, v45, v143, s[0:1]
	v_cmp_gt_i32_e64 s[0:1], v38, v79
	s_and_b64 s[0:1], vcc, s[0:1]
	v_add_u32_e32 v38, 25, v163
	v_max3_f32 v36, v34, s22, v35
	v_cndmask_b32_e64 v158, v46, v143, s[0:1]
	v_cmp_gt_i32_e64 s[0:1], v38, v79
	v_max3_f32 v36, v36, v153, v37
	s_and_b64 s[0:1], vcc, s[0:1]
	v_add_u32_e32 v38, 26, v163
	v_max3_f32 v36, v36, v154, v39
	v_cndmask_b32_e64 v47, v47, v143, s[0:1]
	v_cmp_gt_i32_e64 s[0:1], v38, v79
	v_max3_f32 v36, v36, v155, v156
	s_and_b64 s[0:1], vcc, s[0:1]
	v_add_u32_e32 v38, 27, v163
	v_max3_f32 v36, v36, v42, v43
	v_cndmask_b32_e64 v159, v48, v143, s[0:1]
	v_cmp_gt_i32_e64 s[0:1], v38, v79
	v_max3_f32 v36, v36, v157, v45
	s_and_b64 vcc, vcc, s[0:1]
	v_max3_f32 v36, v36, v158, v47
	v_cndmask_b32_e32 v160, v49, v143, vcc
	v_max3_f32 v36, v36, v159, v160
.Lattn_join_815:
	v_mov_b32_e32 v38, v36
	s_nop 1
	v_permlane32_swap_b32_e32 v36, v38
	v_max_f32_e32 v38, v38, v38
	v_max_f32_e32 v36, v36, v36
	v_max_f32_e32 v36, v36, v38
	v_mul_f32_e32 v36, 0x3e38aa3b, v36
	v_max_f32_e32 v38, v0, v0
	v_max_f32_e32 v71, v38, v36
	v_fma_f32 v34, v34, s23, -v71
	v_exp_f32_e32 v36, v34
	v_fma_f32 v34, v35, s23, -v71
	v_exp_f32_e32 v38, v34
	v_fma_f32 v34, v153, s23, -v71
	v_exp_f32_e32 v40, v34
	v_fma_f32 v34, v37, s23, -v71
	v_exp_f32_e32 v41, v34
	v_fma_f32 v35, v154, s23, -v71
	v_add_f32_e32 v34, 0, v36
	v_exp_f32_e32 v44, v35
	v_fma_f32 v35, v39, s23, -v71
	v_add_f32_e32 v34, v38, v34
	v_exp_f32_e32 v46, v35
	v_fma_f32 v35, v155, s23, -v71
	v_add_f32_e32 v34, v40, v34
	v_exp_f32_e32 v48, v35
	v_fma_f32 v35, v156, s23, -v71
	v_add_f32_e32 v34, v41, v34
	v_exp_f32_e32 v49, v35
	v_add_f32_e32 v34, v44, v34
	v_add_f32_e32 v34, v46, v34
	v_add_f32_e32 v34, v48, v34
	v_add_f32_e32 v153, v49, v34
	v_fma_f32 v34, v42, s23, -v71
	v_exp_f32_e32 v34, v34
	v_fma_f32 v35, v43, s23, -v71
	v_exp_f32_e32 v35, v35
	v_fma_f32 v37, v157, s23, -v71
	v_exp_f32_e32 v37, v37
	v_fma_f32 v39, v45, s23, -v71
	v_exp_f32_e32 v39, v39
	v_add_f32_e32 v42, v34, v153
	v_add_f32_e32 v42, v35, v42
	v_add_f32_e32 v42, v37, v42
	v_add_f32_e32 v153, v39, v42
	v_fma_f32 v42, v158, s23, -v71
	v_exp_f32_e32 v42, v42
	v_fma_f32 v43, v47, s23, -v71
	v_exp_f32_e32 v43, v43
	v_fma_f32 v45, v159, s23, -v71
	v_exp_f32_e32 v45, v45
	v_fma_f32 v47, v160, s23, -v71
	v_exp_f32_e32 v47, v47
	v_sub_f32_e32 v0, v0, v71
	v_add_f32_e32 v153, v42, v153
	v_add_f32_e32 v153, v43, v153
	v_exp_f32_e32 v0, v0
	v_add_f32_e32 v153, v45, v153
	v_add_f32_e32 v153, v47, v153
	v_mov_b32_e32 v154, v153
	s_nop 1
	v_permlane32_swap_b32_e32 v153, v154
	v_cmp_neq_f32_e32 vcc, 1.0, v0
	s_cbranch_vccz .LBB0_814
	v_pk_mul_f32 v[32:33], v[32:33], v[0:1] op_sel_hi:[1,0]
	v_pk_mul_f32 v[30:31], v[30:31], v[0:1] op_sel_hi:[1,0]
	v_pk_mul_f32 v[28:29], v[28:29], v[0:1] op_sel_hi:[1,0]
	v_pk_mul_f32 v[26:27], v[26:27], v[0:1] op_sel_hi:[1,0]
	v_pk_mul_f32 v[24:25], v[24:25], v[0:1] op_sel_hi:[1,0]
	v_pk_mul_f32 v[22:23], v[22:23], v[0:1] op_sel_hi:[1,0]
	v_pk_mul_f32 v[20:21], v[20:21], v[0:1] op_sel_hi:[1,0]
	v_pk_mul_f32 v[18:19], v[18:19], v[0:1] op_sel_hi:[1,0]
	v_pk_mul_f32 v[16:17], v[16:17], v[0:1] op_sel_hi:[1,0]
	v_pk_mul_f32 v[14:15], v[14:15], v[0:1] op_sel_hi:[1,0]
	v_pk_mul_f32 v[12:13], v[12:13], v[0:1] op_sel_hi:[1,0]
	v_pk_mul_f32 v[10:11], v[10:11], v[0:1] op_sel_hi:[1,0]
	v_pk_mul_f32 v[8:9], v[8:9], v[0:1] op_sel_hi:[1,0]
	v_pk_mul_f32 v[6:7], v[6:7], v[0:1] op_sel_hi:[1,0]
	v_pk_mul_f32 v[4:5], v[4:5], v[0:1] op_sel_hi:[1,0]
	v_pk_mul_f32 v[2:3], v[2:3], v[0:1] op_sel_hi:[1,0]
	s_branch .LBB0_814
